# c12 + phase 6 rmsnorm-quant rows: 4 row loads per trip issued together, gains preloaded (counted waits)
# speedup vs baseline: 1.0085x; 1.0031x over previous
.LBB0_1594:
	v_readlane_b32 vcc_lo, v255, 46
	s_cmp_eq_u32 vcc_lo, 2
	s_cbranch_scc1 .LBB0_1625
	s_lshl_b32 s0, s81, 3
	s_add_i32 s8, s80, s0
	s_cmp_gt_i32 s8, 0x80ff
	v_mbcnt_lo_u32_b32 v0, -1, 0
	v_mbcnt_hi_u32_b32 v0, -1, v0
	s_cbranch_scc1 .Lp6_rows_done
	s_waitcnt lgkmcnt(0)
	s_lshl_b32 s34, s38, 3
	s_add_u32 s35, s78, 0xc219000
	s_addc_u32 s36, s79, 0
	v_lshlrev_b32_e32 v6, 2, v0
	s_add_u32 s37, s78, 0x91b9000
	v_ashrrev_i32_e32 v7, 31, v6
	s_addc_u32 s39, s79, 0
	v_lshl_add_u64 v[4:5], s[78:79], 0, v[6:7]
	s_mov_b64 s[0:1], 0xa1d9000
	s_ashr_i32 s9, s8, 31
	s_lshl_b32 s10, s38, 5
	v_lshl_add_u64 v[4:5], v[4:5], 0, s[0:1]
	s_lshl_b32 s40, s38, 4
	s_lshl_b64 s[0:1], s[8:9], 2
	v_readlane_b32 s12, v254, 18
	s_add_u32 s42, s0, 0x91b9000
	v_readlane_b32 s24, v254, 30
	v_readlane_b32 s25, v254, 31
	s_addc_u32 s43, s1, 0
	s_lshl_b64 s[0:1], s[8:9], 10
	v_cmp_eq_u32_e64 s[2:3], 0, v0
	v_readlane_b32 s13, v254, 19
	v_readlane_b32 s14, v254, 20
	v_readlane_b32 s15, v254, 21
	v_readlane_b32 s16, v254, 22
	v_readlane_b32 s17, v254, 23
	v_readlane_b32 s18, v254, 24
	v_readlane_b32 s19, v254, 25
	v_lshl_add_u64 v[0:1], v[6:7], 2, s[24:25]
	v_lshlrev_b64 v[8:9], 1, v[6:7]
	s_ashr_i32 s11, s10, 31
	v_lshl_add_u64 v[6:7], s[0:1], 0, v[6:7]
	s_lshl_b64 s[0:1], s[8:9], 11
	v_lshl_add_u64 v[2:3], s[6:7], 0, v[8:9]
	s_mul_i32 s41, s38, 24
	s_lshl_b64 s[6:7], s[10:11], 2
	s_lshl_b64 s[12:13], s[10:11], 10
	s_lshl_b64 s[14:15], s[8:9], 3
	s_lshl_b64 s[16:17], s[10:11], 3
	v_lshl_add_u64 v[8:9], s[0:1], 0, v[8:9]
	s_lshl_b64 s[18:19], s[10:11], 11
	v_mov_b32_e32 v68, 0x358637bd
	s_mov_b32 s9, 0x800000
	v_mov_b32_e32 v69, 0
	s_mov_b32 s11, 0x42fe0000
	s_mov_b32 s44, 0xa1d9000
	v_mov_b32_e32 v70, 0xc219000
	v_mov_b32_e32 v71, 0x8000
	v_mov_b32_e32 v72, 0x800000
	v_readlane_b32 s20, v254, 26
	v_readlane_b32 s21, v254, 27
	v_readlane_b32 s22, v254, 28
	v_readlane_b32 s23, v254, 29
	v_readlane_b32 s26, v254, 32
	v_readlane_b32 s27, v254, 33
	global_load_dwordx4 v[104:107], v[0:1], off
	global_load_dwordx4 v[108:111], v[0:1], off offset:1024
	global_load_dwordx4 v[112:115], v[0:1], off offset:2048
	global_load_dwordx4 v[116:119], v[0:1], off offset:3072
	s_waitcnt vmcnt(0)
	s_branch .LBB0_1598

.LBB0_1598:
	v_lshl_add_u64 v[58:59], s[78:79], 0, v[8:9]
	v_add_co_u32_e32 v66, vcc, 0x18931000, v58
	s_add_i32 s26, s34, s8
	s_nop 0
	v_addc_co_u32_e32 v67, vcc, 0, v59, vcc
	global_load_dwordx2 v[64:65], v[66:67], off
	global_load_dwordx2 v[62:63], v[66:67], off offset:512
	global_load_dwordx2 v[58:59], v[66:67], off offset:1024
	global_load_dwordx2 v[60:61], v[66:67], off offset:1536
	s_cmp_lt_i32 s26, 0x8100
	s_cselect_b64 s[30:31], -1, 0
	s_cmp_gt_i32 s26, 0x80ff
	s_cbranch_scc1 .LBB0_1600
	s_ashr_i32 s27, s26, 31
	s_lshl_b64 s[0:1], s[26:27], 11
	v_lshl_add_u64 v[30:31], v[2:3], 0, s[0:1]
	global_load_dwordx2 v[36:37], v[30:31], off
	global_load_dwordx2 v[46:47], v[30:31], off offset:512
	global_load_dwordx2 v[50:51], v[30:31], off offset:1024
	global_load_dwordx2 v[98:99], v[30:31], off offset:1536
.LBB0_1600:
	s_add_i32 s22, s40, s8
	s_cmp_lt_i32 s22, 0x8100
	s_cselect_b64 s[28:29], -1, 0
	s_cmp_gt_i32 s22, 0x80ff
	s_cbranch_scc1 .LBB0_1602
	s_ashr_i32 s23, s22, 31
	s_lshl_b64 s[0:1], s[22:23], 11
	v_lshl_add_u64 v[14:15], v[2:3], 0, s[0:1]
	global_load_dwordx2 v[20:21], v[14:15], off
	global_load_dwordx2 v[32:33], v[14:15], off offset:512
	global_load_dwordx2 v[38:39], v[14:15], off offset:1024
	global_load_dwordx2 v[100:101], v[14:15], off offset:1536
.LBB0_1602:
	s_add_i32 s20, s41, s8
	s_cmp_lt_i32 s20, 0x8100
	s_cselect_b64 s[24:25], -1, 0
	s_cmp_gt_i32 s20, 0x80ff
	s_cbranch_scc1 .LBB0_1604
	s_ashr_i32 s21, s20, 31
	s_lshl_b64 s[0:1], s[20:21], 11
	v_lshl_add_u64 v[10:11], v[2:3], 0, s[0:1]
	global_load_dwordx2 v[12:13], v[10:11], off
	global_load_dwordx2 v[16:17], v[10:11], off offset:512
	global_load_dwordx2 v[22:23], v[10:11], off offset:1024
	global_load_dwordx2 v[102:103], v[10:11], off offset:1536
.LBB0_1604:
	s_waitcnt vmcnt(0)
	s_and_b64 vcc, exec, s[30:31]
	s_cbranch_vccz .Lq6_u2
	v_lshlrev_b32_e32 v49, 16, v36
	v_and_b32_e32 v48, 0xffff0000, v36
	v_lshlrev_b32_e32 v53, 16, v37
	v_and_b32_e32 v52, 0xffff0000, v37
	v_lshlrev_b32_e32 v55, 16, v46
	v_and_b32_e32 v54, 0xffff0000, v46
	v_lshlrev_b32_e32 v57, 16, v47
	v_and_b32_e32 v56, 0xffff0000, v47
	v_lshlrev_b32_e32 v31, 16, v50
	v_lshlrev_b32_e32 v30, 16, v98
	v_and_b32_e32 v37, 0xffff0000, v50
	v_and_b32_e32 v36, 0xffff0000, v98
	v_lshlrev_b32_e32 v47, 16, v51
	v_lshlrev_b32_e32 v46, 16, v99
	v_and_b32_e32 v51, 0xffff0000, v51
	v_and_b32_e32 v50, 0xffff0000, v99
.Lq6_u2:
	s_and_b64 vcc, exec, s[28:29]
	s_cbranch_vccz .Lq6_u3
	v_lshlrev_b32_e32 v35, 16, v20
	v_and_b32_e32 v34, 0xffff0000, v20
	v_lshlrev_b32_e32 v41, 16, v21
	v_and_b32_e32 v40, 0xffff0000, v21
	v_lshlrev_b32_e32 v43, 16, v32
	v_and_b32_e32 v42, 0xffff0000, v32
	v_lshlrev_b32_e32 v45, 16, v33
	v_and_b32_e32 v44, 0xffff0000, v33
	v_lshlrev_b32_e32 v15, 16, v38
	v_lshlrev_b32_e32 v14, 16, v100
	v_and_b32_e32 v21, 0xffff0000, v38
	v_and_b32_e32 v20, 0xffff0000, v100
	v_lshlrev_b32_e32 v33, 16, v39
	v_lshlrev_b32_e32 v32, 16, v101
	v_and_b32_e32 v39, 0xffff0000, v39
	v_and_b32_e32 v38, 0xffff0000, v101
.Lq6_u3:
	s_and_b64 vcc, exec, s[24:25]
	s_cbranch_vccz .Lq6_u4
	v_lshlrev_b32_e32 v19, 16, v12
	v_and_b32_e32 v18, 0xffff0000, v12
	v_lshlrev_b32_e32 v25, 16, v13
	v_and_b32_e32 v24, 0xffff0000, v13
	v_lshlrev_b32_e32 v27, 16, v16
	v_and_b32_e32 v26, 0xffff0000, v16
	v_lshlrev_b32_e32 v29, 16, v17
	v_and_b32_e32 v28, 0xffff0000, v17
	v_lshlrev_b32_e32 v11, 16, v22
	v_lshlrev_b32_e32 v10, 16, v102
	v_and_b32_e32 v13, 0xffff0000, v22
	v_and_b32_e32 v12, 0xffff0000, v102
	v_lshlrev_b32_e32 v17, 16, v23
	v_lshlrev_b32_e32 v16, 16, v103
	v_and_b32_e32 v23, 0xffff0000, v23
	v_and_b32_e32 v22, 0xffff0000, v103
.Lq6_u4:
	v_and_b32_e32 v74, 0xffff0000, v64
	v_and_b32_e32 v78, 0xffff0000, v62
	v_lshlrev_b32_e32 v73, 16, v64
	v_lshlrev_b32_e32 v75, 16, v65
	v_and_b32_e32 v76, 0xffff0000, v65
	v_lshlrev_b32_e32 v77, 16, v62
	v_lshlrev_b32_e32 v79, 16, v63
	v_and_b32_e32 v80, 0xffff0000, v63
	v_lshlrev_b32_e32 v65, 16, v60
	v_lshlrev_b32_e32 v64, 16, v58
	v_and_b32_e32 v63, 0xffff0000, v60
	v_and_b32_e32 v62, 0xffff0000, v58
	v_lshlrev_b32_e32 v66, 16, v59
	v_and_b32_e32 v60, 0xffff0000, v59
	v_mul_f32_e32 v58, v74, v74
	v_mul_f32_e32 v59, v78, v78
	v_fmac_f32_e32 v58, v73, v73
	v_fmac_f32_e32 v59, v77, v77
	v_fmac_f32_e32 v58, v75, v75
	v_fmac_f32_e32 v59, v79, v79
	v_fmac_f32_e32 v58, v76, v76
	v_fmac_f32_e32 v59, v80, v80
	v_add_f32_e32 v81, v58, v59
	v_pk_mul_f32 v[58:59], v[62:63], v[62:63]
	v_lshlrev_b32_e32 v67, 16, v61
	v_pk_fma_f32 v[58:59], v[64:65], v[64:65], v[58:59]
	v_and_b32_e32 v61, 0xffff0000, v61
	v_pk_fma_f32 v[58:59], v[66:67], v[66:67], v[58:59]
	s_nop 0
	v_pk_fma_f32 v[58:59], v[60:61], v[60:61], v[58:59]
	s_nop 0
	v_add_f32_e32 v58, v81, v58
	v_add_f32_e32 v58, v58, v59
	s_nop 1
	v_add_f32_dpp v58, v58, v58 quad_perm:[1,0,3,2] row_mask:0xf bank_mask:0xf bound_ctrl:1
	s_nop 1
	v_add_f32_dpp v58, v58, v58 quad_perm:[2,3,0,1] row_mask:0xf bank_mask:0xf bound_ctrl:1
	s_nop 1
	v_add_f32_dpp v58, v58, v58 row_half_mirror row_mask:0xf bank_mask:0xf bound_ctrl:1
	s_nop 1
	v_add_f32_dpp v58, v58, v58 row_mirror row_mask:0xf bank_mask:0xf bound_ctrl:1
	s_nop 0
	v_readlane_b32 s1, v58, 16
	v_readlane_b32 s0, v58, 0
	s_nop 0
	v_mov_b32_e32 v59, s1
	v_add_f32_e32 v59, s0, v59
	v_readlane_b32 s0, v58, 32
	s_nop 1
	v_add_f32_e32 v59, s0, v59
	v_readlane_b32 s0, v58, 48
	s_nop 1
	v_add_f32_e32 v58, s0, v59
	v_fmamk_f32 v58, v58, 0x3a800000, v68
	v_mul_f32_e32 v59, 0x4b800000, v58
	v_cmp_gt_f32_e32 vcc, s9, v58
	s_nop 1
	v_cndmask_b32_e32 v58, v58, v59, vcc
	v_rsq_f32_e32 v58, v58
	s_nop 0
	v_mul_f32_e32 v59, 0x45800000, v58
	v_cndmask_b32_e32 v58, v58, v59, vcc
	s_and_saveexec_b64 s[0:1], s[2:3]
	s_cbranch_execz .LBB0_1606
	s_add_u32 s46, s78, s42
	s_addc_u32 s47, s79, s43
	global_store_dword v69, v58, s[46:47]
.LBB0_1606:
	s_or_b64 exec, exec, s[0:1]
	v_mul_f32_e32 v59, v58, v73
	v_mul_f32_e32 v73, v58, v74
	v_mul_f32_e32 v74, v58, v75
	v_mul_f32_e32 v75, v58, v76
	v_mul_f32_e32 v76, v58, v77
	v_mul_f32_e32 v77, v58, v78
	v_mul_f32_e32 v78, v58, v79
	v_mul_f32_e32 v79, v58, v80
	v_mul_f32_e32 v64, v58, v64
	v_mul_f32_e32 v62, v58, v62
	v_mul_f32_e32 v66, v58, v66
	v_mul_f32_e32 v80, v58, v60
	v_mul_f32_e32 v65, v58, v65
	v_mul_f32_e32 v63, v58, v63
	v_mul_f32_e32 v67, v58, v67
	v_mul_f32_e32 v58, v58, v61
	v_lshl_add_u64 v[60:61], s[78:79], 0, v[6:7]
	v_add_co_u32_e32 v60, vcc, s44, v60
	s_nop 0
	v_mul_f32_e32 v74, v74, v106
	v_mul_f32_e32 v75, v75, v107
	s_nop 0
	v_mul_f32_e32 v78, v78, v110
	v_mul_f32_e32 v79, v79, v111
	v_mul_f32_e32 v59, v59, v104
	v_mul_f32_e32 v73, v73, v105
	v_mul_f32_e32 v76, v76, v108
	v_mul_f32_e32 v77, v77, v109
	s_nop 0
	v_mul_f32_e32 v66, v66, v114
	v_mul_f32_e32 v80, v80, v115
	s_nop 0
	v_mul_f32_e32 v67, v67, v118
	v_mul_f32_e32 v81, v58, v119
	v_max_f32_e64 v58, |v74|, |v75|
	v_max_f32_e64 v82, |v78|, |v79|
	v_mul_f32_e32 v64, v64, v112
	v_mul_f32_e32 v62, v62, v113
	v_mul_f32_e32 v65, v65, v116
	v_mul_f32_e32 v63, v63, v117
	v_max_f32_e64 v83, |v66|, |v80|
	v_max_f32_e64 v84, |v67|, |v81|
	v_max3_f32 v58, |v59|, |v73|, v58
	v_max3_f32 v82, |v76|, |v77|, v82
	v_max3_f32 v83, |v64|, |v62|, v83
	v_max3_f32 v84, |v65|, |v63|, v84
	v_max3_f32 v58, v58, 0, v82
	v_max3_f32 v58, v58, v83, v84
	v_addc_co_u32_e32 v61, vcc, 0, v61, vcc
	s_nop 0
	v_mov_b32_dpp v82, v58 quad_perm:[1,0,3,2] row_mask:0xf bank_mask:0xf bound_ctrl:1
	v_max_f32_e32 v82, v82, v82
	v_max_f32_e32 v58, v58, v82
	s_nop 1
	v_mov_b32_dpp v82, v58 quad_perm:[2,3,0,1] row_mask:0xf bank_mask:0xf bound_ctrl:1
	v_max_f32_e32 v82, v82, v82
	v_max_f32_e32 v58, v58, v82
	s_nop 1
	v_mov_b32_dpp v82, v58 row_half_mirror row_mask:0xf bank_mask:0xf bound_ctrl:1
	v_max_f32_e32 v82, v82, v82
	v_max_f32_e32 v58, v58, v82
	s_nop 1
	v_mov_b32_dpp v82, v58 row_mirror row_mask:0xf bank_mask:0xf bound_ctrl:1
	v_max_f32_e32 v82, v82, v82
	v_max_f32_e32 v58, v58, v82
	s_nop 0
	v_readlane_b32 s21, v58, 32
	v_readlane_b32 s23, v58, 48
	v_readlane_b32 s0, v58, 0
	v_readlane_b32 s1, v58, 16
	v_max_f32_e64 v58, s23, s23
	v_max_f32_e64 v82, s21, s21
	v_mov_b32_e32 v83, s1
	v_max_f32_e32 v58, v82, v58
	v_max3_f32 v58, s0, v83, v58
	v_div_scale_f32 v82, s[0:1], v58, v58, s11
	v_rcp_f32_e32 v83, v82
	v_div_scale_f32 v84, vcc, s11, v58, s11
	v_fma_f32 v85, -v82, v83, 1.0
	v_fmac_f32_e32 v83, v85, v83
	v_mul_f32_e32 v85, v84, v83
	v_fma_f32 v86, -v82, v85, v84
	v_fmac_f32_e32 v85, v86, v83
	v_fma_f32 v82, -v82, v85, v84
	v_div_fmas_f32 v82, v82, v83, v85
	v_div_fixup_f32 v82, v82, v58, s11
	v_cmp_lt_f32_e32 vcc, 0, v58
	s_nop 1
	v_cndmask_b32_e32 v82, 0, v82, vcc
	v_mul_f32_e32 v59, v59, v82
	v_mul_f32_e32 v73, v73, v82
	v_mul_f32_e32 v75, v75, v82
	v_mul_f32_e32 v74, v74, v82
	v_rndne_f32_e32 v59, v59
	v_rndne_f32_e32 v73, v73
	v_rndne_f32_e32 v75, v75
	v_mul_f32_e32 v76, v76, v82
	v_mul_f32_e32 v77, v77, v82
	v_rndne_f32_e32 v74, v74
	v_cvt_i32_f32_e32 v59, v59
	v_cvt_i32_f32_e32 v73, v73
	v_cvt_i32_f32_e32 v75, v75
	v_mul_f32_e32 v78, v78, v82
	v_mul_f32_e32 v79, v79, v82
	v_rndne_f32_e32 v76, v76
	v_rndne_f32_e32 v77, v77
	v_cvt_i32_f32_e32 v74, v74
	v_rndne_f32_e32 v78, v78
	v_rndne_f32_e32 v79, v79
	v_cvt_i32_f32_e32 v76, v76
	v_cvt_i32_f32_e32 v77, v77
	v_cvt_i32_f32_e32 v78, v78
	v_cvt_i32_f32_e32 v79, v79
	v_add_u32_e32 v83, v59, v73
	v_add_u32_e32 v59, 0x80, v59
	v_lshl_add_u32 v73, v73, 8, v71
	v_lshlrev_b32_e32 v85, 24, v75
	v_lshl_add_u32 v84, v74, 16, v72
	v_add3_u32 v74, v83, v74, v75
	v_or_b32_e32 v59, v73, v59
	v_xor_b32_e32 v73, 0x80000000, v85
	v_or3_b32 v59, v59, v84, v73
	v_add3_u32 v73, v74, v76, v77
	v_add_u32_e32 v86, 0x80, v76
	global_store_dword v[60:61], v59, off
	v_add3_u32 v59, v73, v78, v79
	v_lshl_add_u32 v73, v77, 8, v71
	v_lshlrev_b32_e32 v75, 24, v79
	v_mul_f32_e32 v64, v64, v82
	v_mul_f32_e32 v62, v62, v82
	v_or_b32_e32 v73, v73, v86
	v_lshl_add_u32 v74, v78, 16, v72
	v_xor_b32_e32 v75, 0x80000000, v75
	v_rndne_f32_e32 v64, v64
	v_rndne_f32_e32 v62, v62
	v_mul_f32_e32 v66, v66, v82
	v_mul_f32_e32 v76, v80, v82
	v_cvt_i32_f32_e32 v64, v64
	v_cvt_i32_f32_e32 v62, v62
	v_rndne_f32_e32 v66, v66
	v_rndne_f32_e32 v76, v76
	v_or3_b32 v73, v73, v74, v75
	v_mul_f32_e32 v65, v65, v82
	v_mul_f32_e32 v63, v63, v82
	v_cvt_i32_f32_e32 v66, v66
	v_cvt_i32_f32_e32 v76, v76
	global_store_dword v[60:61], v73, off offset:256
	v_rndne_f32_e32 v65, v65
	v_rndne_f32_e32 v63, v63
	v_mul_f32_e32 v67, v67, v82
	v_mul_f32_e32 v73, v81, v82
	v_cvt_i32_f32_e32 v65, v65
	v_cvt_i32_f32_e32 v63, v63
	v_rndne_f32_e32 v67, v67
	v_rndne_f32_e32 v73, v73
	v_cvt_i32_f32_e32 v67, v67
	v_cvt_i32_f32_e32 v73, v73
	v_add3_u32 v59, v59, v64, v62
	v_add3_u32 v59, v59, v66, v76
	v_add3_u32 v59, v59, v65, v63
	v_add3_u32 v59, v59, v67, v73
	v_cvt_f32_i32_e32 v59, v59
	v_add_u32_e32 v64, 0x80, v64
	v_lshl_add_u32 v62, v62, 8, v71
	v_or_b32_e32 v62, v62, v64
	v_lshl_add_u32 v64, v66, 16, v72
	v_lshlrev_b32_e32 v66, 24, v76
	v_xor_b32_e32 v66, 0x80000000, v66
	v_add_f32_dpp v59, v59, v59 quad_perm:[1,0,3,2] row_mask:0xf bank_mask:0xf bound_ctrl:1
	v_or3_b32 v62, v62, v64, v66
	global_store_dword v[60:61], v62, off offset:512
	v_add_f32_dpp v59, v59, v59 quad_perm:[2,3,0,1] row_mask:0xf bank_mask:0xf bound_ctrl:1
	v_add_u32_e32 v62, 0x80, v65
	v_lshl_add_u32 v63, v63, 8, v71
	v_lshlrev_b32_e32 v64, 24, v73
	v_add_f32_dpp v59, v59, v59 row_half_mirror row_mask:0xf bank_mask:0xf bound_ctrl:1
	v_or_b32_e32 v62, v63, v62
	v_lshl_add_u32 v63, v67, 16, v72
	v_xor_b32_e32 v64, 0x80000000, v64
	v_add_f32_dpp v59, v59, v59 row_mirror row_mask:0xf bank_mask:0xf bound_ctrl:1
	v_or3_b32 v62, v62, v63, v64
	v_readlane_b32 s21, v59, 0
	v_readlane_b32 s45, v59, 16
	v_readlane_b32 s23, v59, 32
	v_readlane_b32 s27, v59, 48
	global_store_dword v[60:61], v62, off offset:768
	s_and_saveexec_b64 s[0:1], s[2:3]
	s_cbranch_execz .LBB0_1614
	v_mov_b32_e32 v59, s45
	v_add_f32_e32 v59, s21, v59
	s_add_u32 s46, s78, s14
	v_add_f32_e32 v59, s23, v59
	s_addc_u32 s47, s79, s15
	v_mul_f32_e32 v58, 0x3c010204, v58
	v_add_f32_e32 v59, s27, v59
	global_store_dwordx2 v70, v[58:59], s[46:47]
	s_or_b64 exec, exec, s[0:1]
	s_andn2_b64 vcc, exec, s[30:31]
	s_cbranch_vccz .LBB0_1615

.LBB0_1611:
	s_or_b64 exec, exec, s[0:1]
	v_mul_f32_e32 v82, v41, v58
	v_mul_f32_e32 v83, v40, v58
	v_mul_f32_e32 v86, v45, v58
	v_mul_f32_e32 v87, v44, v58
	v_mul_f32_e32 v59, v35, v58
	v_mul_f32_e32 v73, v34, v58
	v_mul_f32_e32 v84, v43, v58
	v_mul_f32_e32 v85, v42, v58
	v_mul_f32_e32 v88, v15, v58
	v_mul_f32_e32 v89, v21, v58
	v_mul_f32_e32 v90, v33, v58
	v_mul_f32_e32 v91, v39, v58
	v_mul_f32_e32 v92, v14, v58
	v_mul_f32_e32 v93, v20, v58
	v_mul_f32_e32 v94, v32, v58
	v_mul_f32_e32 v58, v38, v58
	s_lshl_b64 s[0:1], s[22:23], 10
	s_nop 0
	v_mul_f32_e32 v62, v82, v106
	v_mul_f32_e32 v63, v83, v107
	s_nop 0
	v_mul_f32_e32 v66, v86, v110
	v_mul_f32_e32 v67, v87, v111
	v_mul_f32_e32 v59, v59, v104
	v_mul_f32_e32 v73, v73, v105
	v_mul_f32_e32 v64, v84, v108
	v_mul_f32_e32 v65, v85, v109
	s_nop 0
	v_mul_f32_e32 v76, v90, v114
	v_mul_f32_e32 v77, v91, v115
	s_nop 0
	v_mul_f32_e32 v80, v94, v118
	v_mul_f32_e32 v81, v58, v119
	v_max_f32_e64 v58, |v62|, |v63|
	v_max_f32_e64 v60, |v66|, |v67|
	v_mul_f32_e32 v74, v88, v112
	v_mul_f32_e32 v75, v89, v113
	v_mul_f32_e32 v78, v92, v116
	v_mul_f32_e32 v79, v93, v117
	v_max_f32_e64 v61, |v76|, |v77|
	v_max_f32_e64 v82, |v80|, |v81|
	v_max3_f32 v58, |v59|, |v73|, v58
	v_max3_f32 v60, |v64|, |v65|, v60
	v_max3_f32 v61, |v74|, |v75|, v61
	v_max3_f32 v82, |v78|, |v79|, v82
	v_max3_f32 v58, v58, 0, v60
	v_max3_f32 v58, v58, v61, v82
	s_nop 1
	v_mov_b32_dpp v60, v58 quad_perm:[1,0,3,2] row_mask:0xf bank_mask:0xf bound_ctrl:1
	v_max_f32_e32 v60, v60, v60
	v_max_f32_e32 v58, v58, v60
	s_nop 1
	v_mov_b32_dpp v60, v58 quad_perm:[2,3,0,1] row_mask:0xf bank_mask:0xf bound_ctrl:1
	v_max_f32_e32 v60, v60, v60
	v_max_f32_e32 v58, v58, v60
	s_nop 1
	v_mov_b32_dpp v60, v58 row_half_mirror row_mask:0xf bank_mask:0xf bound_ctrl:1
	v_max_f32_e32 v60, v60, v60
	v_max_f32_e32 v58, v58, v60
	s_nop 1
	v_mov_b32_dpp v60, v58 row_mirror row_mask:0xf bank_mask:0xf bound_ctrl:1
	v_max_f32_e32 v60, v60, v60
	v_max_f32_e32 v58, v58, v60
	s_nop 0
	v_readlane_b32 s27, v58, 32
	v_readlane_b32 s28, v58, 48
	v_readlane_b32 s21, v58, 0
	v_readlane_b32 s26, v58, 16
	v_max_f32_e64 v58, s28, s28
	v_max_f32_e64 v60, s27, s27
	v_mov_b32_e32 v61, s26
	v_max_f32_e32 v58, v60, v58
	v_max3_f32 v58, s21, v61, v58
	v_div_scale_f32 v82, s[26:27], v58, v58, s11
	v_rcp_f32_e32 v83, v82
	v_div_scale_f32 v84, vcc, s11, v58, s11
	v_lshl_add_u64 v[60:61], v[4:5], 0, s[0:1]
	v_fma_f32 v85, -v82, v83, 1.0
	v_fmac_f32_e32 v83, v85, v83
	v_mul_f32_e32 v85, v84, v83
	v_fma_f32 v86, -v82, v85, v84
	v_fmac_f32_e32 v85, v86, v83
	v_fma_f32 v82, -v82, v85, v84
	v_div_fmas_f32 v82, v82, v83, v85
	v_div_fixup_f32 v82, v82, v58, s11
	v_cmp_lt_f32_e32 vcc, 0, v58
	s_nop 1
	v_cndmask_b32_e32 v82, 0, v82, vcc
	v_mul_f32_e32 v59, v59, v82
	v_mul_f32_e32 v73, v73, v82
	v_mul_f32_e32 v63, v63, v82
	v_mul_f32_e32 v62, v62, v82
	v_rndne_f32_e32 v59, v59
	v_rndne_f32_e32 v73, v73
	v_rndne_f32_e32 v63, v63
	v_mul_f32_e32 v64, v64, v82
	v_mul_f32_e32 v65, v65, v82
	v_rndne_f32_e32 v62, v62
	v_cvt_i32_f32_e32 v59, v59
	v_cvt_i32_f32_e32 v73, v73
	v_cvt_i32_f32_e32 v63, v63
	v_mul_f32_e32 v66, v66, v82
	v_mul_f32_e32 v67, v67, v82
	v_rndne_f32_e32 v64, v64
	v_rndne_f32_e32 v65, v65
	v_cvt_i32_f32_e32 v62, v62
	v_rndne_f32_e32 v66, v66
	v_rndne_f32_e32 v67, v67
	v_cvt_i32_f32_e32 v64, v64
	v_cvt_i32_f32_e32 v65, v65
	v_cvt_i32_f32_e32 v66, v66
	v_cvt_i32_f32_e32 v67, v67
	v_add_u32_e32 v83, v59, v73
	v_add_u32_e32 v59, 0x80, v59
	v_lshl_add_u32 v73, v73, 8, v71
	v_lshlrev_b32_e32 v85, 24, v63
	v_lshl_add_u32 v84, v62, 16, v72
	v_add3_u32 v62, v83, v62, v63
	v_or_b32_e32 v59, v73, v59
	v_xor_b32_e32 v63, 0x80000000, v85
	v_add_u32_e32 v86, 0x80, v64
	v_or3_b32 v59, v59, v84, v63
	v_add3_u32 v62, v62, v64, v65
	v_mul_f32_e32 v63, v74, v82
	v_mul_f32_e32 v64, v75, v82
	v_lshl_add_u32 v87, v65, 8, v71
	v_lshl_add_u32 v88, v66, 16, v72
	global_store_dword v[60:61], v59, off
	v_add3_u32 v59, v62, v66, v67
	v_rndne_f32_e32 v63, v63
	v_rndne_f32_e32 v64, v64
	v_mul_f32_e32 v65, v76, v82
	v_mul_f32_e32 v66, v77, v82
	v_cvt_i32_f32_e32 v63, v63
	v_cvt_i32_f32_e32 v64, v64
	v_rndne_f32_e32 v65, v65
	v_rndne_f32_e32 v66, v66
	v_lshlrev_b32_e32 v62, 24, v67
	v_cvt_i32_f32_e32 v65, v65
	v_cvt_i32_f32_e32 v66, v66
	v_or_b32_e32 v73, v87, v86
	v_xor_b32_e32 v62, 0x80000000, v62
	v_or3_b32 v62, v73, v88, v62
	global_store_dword v[60:61], v62, off offset:256
	v_add3_u32 v59, v59, v63, v64
	v_add_u32_e32 v62, 0x80, v63
	v_lshl_add_u32 v63, v64, 8, v71
	v_add3_u32 v59, v59, v65, v66
	v_or_b32_e32 v62, v63, v62
	v_lshl_add_u32 v63, v65, 16, v72
	v_lshlrev_b32_e32 v64, 24, v66
	v_mul_f32_e32 v65, v78, v82
	v_mul_f32_e32 v66, v79, v82
	v_rndne_f32_e32 v65, v65
	v_rndne_f32_e32 v66, v66
	v_mul_f32_e32 v67, v80, v82
	v_mul_f32_e32 v73, v81, v82
	v_cvt_i32_f32_e32 v65, v65
	v_cvt_i32_f32_e32 v66, v66
	v_rndne_f32_e32 v67, v67
	v_rndne_f32_e32 v73, v73
	v_cvt_i32_f32_e32 v67, v67
	v_cvt_i32_f32_e32 v73, v73
	v_add3_u32 v59, v59, v65, v66
	v_xor_b32_e32 v64, 0x80000000, v64
	v_or3_b32 v62, v62, v63, v64
	v_add3_u32 v59, v59, v67, v73
	v_cvt_f32_i32_e32 v59, v59
	global_store_dword v[60:61], v62, off offset:512
	v_add_u32_e32 v62, 0x80, v65
	v_lshl_add_u32 v63, v66, 8, v71
	v_add_f32_dpp v59, v59, v59 quad_perm:[1,0,3,2] row_mask:0xf bank_mask:0xf bound_ctrl:1
	v_lshlrev_b32_e32 v64, 24, v73
	v_or_b32_e32 v62, v63, v62
	v_add_f32_dpp v59, v59, v59 quad_perm:[2,3,0,1] row_mask:0xf bank_mask:0xf bound_ctrl:1
	v_lshl_add_u32 v63, v67, 16, v72
	v_xor_b32_e32 v64, 0x80000000, v64
	v_add_f32_dpp v59, v59, v59 row_half_mirror row_mask:0xf bank_mask:0xf bound_ctrl:1
	v_or3_b32 v62, v62, v63, v64
	global_store_dword v[60:61], v62, off offset:768
	v_add_f32_dpp v59, v59, v59 row_mirror row_mask:0xf bank_mask:0xf bound_ctrl:1
	s_nop 0
	v_readlane_b32 s21, v59, 0
	v_readlane_b32 s28, v59, 16
	v_readlane_b32 s26, v59, 32
	v_readlane_b32 s27, v59, 48
	s_and_saveexec_b64 s[0:1], s[2:3]
	s_cbranch_execz .LBB0_1613
	v_mov_b32_e32 v59, s28
	s_lshl_b64 s[22:23], s[22:23], 3
	v_add_f32_e32 v59, s21, v59
	s_add_u32 s22, s35, s22
	v_add_f32_e32 v59, s26, v59
	s_addc_u32 s23, s36, s23
	v_mul_f32_e32 v58, 0x3c010204, v58
	v_add_f32_e32 v59, s27, v59
	global_store_dwordx2 v69, v[58:59], s[22:23]

.LBB0_1617:
	s_or_b64 exec, exec, s[0:1]
	v_mul_f32_e32 v82, v53, v58
	v_mul_f32_e32 v83, v52, v58
	v_mul_f32_e32 v86, v57, v58
	v_mul_f32_e32 v87, v56, v58
	v_mul_f32_e32 v59, v49, v58
	v_mul_f32_e32 v73, v48, v58
	v_mul_f32_e32 v84, v55, v58
	v_mul_f32_e32 v85, v54, v58
	v_mul_f32_e32 v88, v31, v58
	v_mul_f32_e32 v89, v37, v58
	v_mul_f32_e32 v90, v47, v58
	v_mul_f32_e32 v91, v51, v58
	v_mul_f32_e32 v92, v30, v58
	v_mul_f32_e32 v93, v36, v58
	v_mul_f32_e32 v94, v46, v58
	v_mul_f32_e32 v58, v50, v58
	s_lshl_b64 s[0:1], s[26:27], 10
	s_nop 0
	v_mul_f32_e32 v62, v82, v106
	v_mul_f32_e32 v63, v83, v107
	s_nop 0
	v_mul_f32_e32 v66, v86, v110
	v_mul_f32_e32 v67, v87, v111
	v_mul_f32_e32 v59, v59, v104
	v_mul_f32_e32 v73, v73, v105
	v_mul_f32_e32 v64, v84, v108
	v_mul_f32_e32 v65, v85, v109
	s_nop 0
	v_mul_f32_e32 v76, v90, v114
	v_mul_f32_e32 v77, v91, v115
	s_nop 0
	v_mul_f32_e32 v80, v94, v118
	v_mul_f32_e32 v81, v58, v119
	v_max_f32_e64 v58, |v62|, |v63|
	v_max_f32_e64 v60, |v66|, |v67|
	v_mul_f32_e32 v74, v88, v112
	v_mul_f32_e32 v75, v89, v113
	v_mul_f32_e32 v78, v92, v116
	v_mul_f32_e32 v79, v93, v117
	v_max_f32_e64 v61, |v76|, |v77|
	v_max_f32_e64 v82, |v80|, |v81|
	v_max3_f32 v58, |v59|, |v73|, v58
	v_max3_f32 v60, |v64|, |v65|, v60
	v_max3_f32 v61, |v74|, |v75|, v61
	v_max3_f32 v82, |v78|, |v79|, v82
	v_max3_f32 v58, v58, 0, v60
	v_max3_f32 v58, v58, v61, v82
	s_nop 1
	v_mov_b32_dpp v60, v58 quad_perm:[1,0,3,2] row_mask:0xf bank_mask:0xf bound_ctrl:1
	v_max_f32_e32 v60, v60, v60
	v_max_f32_e32 v58, v58, v60
	s_nop 1
	v_mov_b32_dpp v60, v58 quad_perm:[2,3,0,1] row_mask:0xf bank_mask:0xf bound_ctrl:1
	v_max_f32_e32 v60, v60, v60
	v_max_f32_e32 v58, v58, v60
	s_nop 1
	v_mov_b32_dpp v60, v58 row_half_mirror row_mask:0xf bank_mask:0xf bound_ctrl:1
	v_max_f32_e32 v60, v60, v60
	v_max_f32_e32 v58, v58, v60
	s_nop 1
	v_mov_b32_dpp v60, v58 row_mirror row_mask:0xf bank_mask:0xf bound_ctrl:1
	v_max_f32_e32 v60, v60, v60
	v_max_f32_e32 v58, v58, v60
	s_nop 0
	v_readlane_b32 s30, v58, 32
	v_readlane_b32 s31, v58, 48
	v_readlane_b32 s21, v58, 0
	v_readlane_b32 s23, v58, 16
	v_max_f32_e64 v58, s31, s31
	v_max_f32_e64 v60, s30, s30
	v_mov_b32_e32 v61, s23
	v_max_f32_e32 v58, v60, v58
	v_max3_f32 v58, s21, v61, v58
	v_div_scale_f32 v82, s[30:31], v58, v58, s11
	v_rcp_f32_e32 v83, v82
	v_div_scale_f32 v84, vcc, s11, v58, s11
	v_lshl_add_u64 v[60:61], v[4:5], 0, s[0:1]
	v_fma_f32 v85, -v82, v83, 1.0
	v_fmac_f32_e32 v83, v85, v83
	v_mul_f32_e32 v85, v84, v83
	v_fma_f32 v86, -v82, v85, v84
	v_fmac_f32_e32 v85, v86, v83
	v_fma_f32 v82, -v82, v85, v84
	v_div_fmas_f32 v82, v82, v83, v85
	v_div_fixup_f32 v82, v82, v58, s11
	v_cmp_lt_f32_e32 vcc, 0, v58
	s_nop 1
	v_cndmask_b32_e32 v82, 0, v82, vcc
	v_mul_f32_e32 v59, v59, v82
	v_mul_f32_e32 v73, v73, v82
	v_mul_f32_e32 v63, v63, v82
	v_mul_f32_e32 v62, v62, v82
	v_rndne_f32_e32 v59, v59
	v_rndne_f32_e32 v73, v73
	v_rndne_f32_e32 v63, v63
	v_mul_f32_e32 v64, v64, v82
	v_mul_f32_e32 v65, v65, v82
	v_rndne_f32_e32 v62, v62
	v_cvt_i32_f32_e32 v59, v59
	v_cvt_i32_f32_e32 v73, v73
	v_cvt_i32_f32_e32 v63, v63
	v_mul_f32_e32 v66, v66, v82
	v_mul_f32_e32 v67, v67, v82
	v_rndne_f32_e32 v64, v64
	v_rndne_f32_e32 v65, v65
	v_cvt_i32_f32_e32 v62, v62
	v_rndne_f32_e32 v66, v66
	v_rndne_f32_e32 v67, v67
	v_cvt_i32_f32_e32 v64, v64
	v_cvt_i32_f32_e32 v65, v65
	v_cvt_i32_f32_e32 v66, v66
	v_cvt_i32_f32_e32 v67, v67
	v_add_u32_e32 v83, v59, v73
	v_add_u32_e32 v59, 0x80, v59
	v_lshl_add_u32 v73, v73, 8, v71
	v_lshlrev_b32_e32 v85, 24, v63
	v_lshl_add_u32 v84, v62, 16, v72
	v_add3_u32 v62, v83, v62, v63
	v_or_b32_e32 v59, v73, v59
	v_xor_b32_e32 v63, 0x80000000, v85
	v_add_u32_e32 v86, 0x80, v64
	v_or3_b32 v59, v59, v84, v63
	v_add3_u32 v62, v62, v64, v65
	v_mul_f32_e32 v63, v74, v82
	v_mul_f32_e32 v64, v75, v82
	v_lshl_add_u32 v87, v65, 8, v71
	v_lshl_add_u32 v88, v66, 16, v72
	global_store_dword v[60:61], v59, off
	v_add3_u32 v59, v62, v66, v67
	v_rndne_f32_e32 v63, v63
	v_rndne_f32_e32 v64, v64
	v_mul_f32_e32 v65, v76, v82
	v_mul_f32_e32 v66, v77, v82
	v_cvt_i32_f32_e32 v63, v63
	v_cvt_i32_f32_e32 v64, v64
	v_rndne_f32_e32 v65, v65
	v_rndne_f32_e32 v66, v66
	v_lshlrev_b32_e32 v62, 24, v67
	v_cvt_i32_f32_e32 v65, v65
	v_cvt_i32_f32_e32 v66, v66
	v_or_b32_e32 v73, v87, v86
	v_xor_b32_e32 v62, 0x80000000, v62
	v_or3_b32 v62, v73, v88, v62
	global_store_dword v[60:61], v62, off offset:256
	v_add3_u32 v59, v59, v63, v64
	v_add_u32_e32 v62, 0x80, v63
	v_lshl_add_u32 v63, v64, 8, v71
	v_add3_u32 v59, v59, v65, v66
	v_or_b32_e32 v62, v63, v62
	v_lshl_add_u32 v63, v65, 16, v72
	v_lshlrev_b32_e32 v64, 24, v66
	v_mul_f32_e32 v65, v78, v82
	v_mul_f32_e32 v66, v79, v82
	v_rndne_f32_e32 v65, v65
	v_rndne_f32_e32 v66, v66
	v_mul_f32_e32 v67, v80, v82
	v_mul_f32_e32 v73, v81, v82
	v_cvt_i32_f32_e32 v65, v65
	v_cvt_i32_f32_e32 v66, v66
	v_rndne_f32_e32 v67, v67
	v_rndne_f32_e32 v73, v73
	v_cvt_i32_f32_e32 v67, v67
	v_cvt_i32_f32_e32 v73, v73
	v_add3_u32 v59, v59, v65, v66
	v_xor_b32_e32 v64, 0x80000000, v64
	v_or3_b32 v62, v62, v63, v64
	v_add3_u32 v59, v59, v67, v73
	v_cvt_f32_i32_e32 v59, v59
	global_store_dword v[60:61], v62, off offset:512
	v_add_u32_e32 v62, 0x80, v65
	v_lshl_add_u32 v63, v66, 8, v71
	v_add_f32_dpp v59, v59, v59 quad_perm:[1,0,3,2] row_mask:0xf bank_mask:0xf bound_ctrl:1
	v_lshlrev_b32_e32 v64, 24, v73
	v_or_b32_e32 v62, v63, v62
	v_add_f32_dpp v59, v59, v59 quad_perm:[2,3,0,1] row_mask:0xf bank_mask:0xf bound_ctrl:1
	v_lshl_add_u32 v63, v67, 16, v72
	v_xor_b32_e32 v64, 0x80000000, v64
	v_add_f32_dpp v59, v59, v59 row_half_mirror row_mask:0xf bank_mask:0xf bound_ctrl:1
	v_or3_b32 v62, v62, v63, v64
	global_store_dword v[60:61], v62, off offset:768
	v_add_f32_dpp v59, v59, v59 row_mirror row_mask:0xf bank_mask:0xf bound_ctrl:1
	s_nop 0
	v_readlane_b32 s21, v59, 0
	v_readlane_b32 s31, v59, 16
	v_readlane_b32 s23, v59, 32
	v_readlane_b32 s30, v59, 48
	s_and_saveexec_b64 s[0:1], s[2:3]
	s_cbranch_execz .LBB0_1619
	v_mov_b32_e32 v59, s31
	s_lshl_b64 s[26:27], s[26:27], 3
	v_add_f32_e32 v59, s21, v59
	s_add_u32 s26, s35, s26
	v_add_f32_e32 v59, s23, v59
	s_addc_u32 s27, s36, s27
	v_mul_f32_e32 v58, 0x3c010204, v58
	v_add_f32_e32 v59, s30, v59
	global_store_dwordx2 v69, v[58:59], s[26:27]

.LBB0_1623:
	s_or_b64 exec, exec, s[0:1]
	v_mul_f32_e32 v82, v25, v58
	v_mul_f32_e32 v83, v24, v58
	v_mul_f32_e32 v86, v29, v58
	v_mul_f32_e32 v87, v28, v58
	v_mul_f32_e32 v59, v19, v58
	v_mul_f32_e32 v73, v18, v58
	v_mul_f32_e32 v84, v27, v58
	v_mul_f32_e32 v85, v26, v58
	v_mul_f32_e32 v88, v11, v58
	v_mul_f32_e32 v89, v13, v58
	v_mul_f32_e32 v90, v17, v58
	v_mul_f32_e32 v91, v23, v58
	v_mul_f32_e32 v92, v10, v58
	v_mul_f32_e32 v93, v12, v58
	v_mul_f32_e32 v94, v16, v58
	v_mul_f32_e32 v58, v22, v58
	s_lshl_b64 s[0:1], s[20:21], 10
	s_nop 0
	v_mul_f32_e32 v62, v82, v106
	v_mul_f32_e32 v63, v83, v107
	s_nop 0
	v_mul_f32_e32 v66, v86, v110
	v_mul_f32_e32 v67, v87, v111
	v_mul_f32_e32 v59, v59, v104
	v_mul_f32_e32 v73, v73, v105
	v_mul_f32_e32 v64, v84, v108
	v_mul_f32_e32 v65, v85, v109
	s_nop 0
	v_mul_f32_e32 v76, v90, v114
	v_mul_f32_e32 v77, v91, v115
	s_nop 0
	v_mul_f32_e32 v80, v94, v118
	v_mul_f32_e32 v81, v58, v119
	v_max_f32_e64 v58, |v62|, |v63|
	v_max_f32_e64 v60, |v66|, |v67|
	v_mul_f32_e32 v74, v88, v112
	v_mul_f32_e32 v75, v89, v113
	v_mul_f32_e32 v78, v92, v116
	v_mul_f32_e32 v79, v93, v117
	v_max_f32_e64 v61, |v76|, |v77|
	v_max_f32_e64 v82, |v80|, |v81|
	v_max3_f32 v58, |v59|, |v73|, v58
	v_max3_f32 v60, |v64|, |v65|, v60
	v_max3_f32 v61, |v74|, |v75|, v61
	v_max3_f32 v82, |v78|, |v79|, v82
	v_max3_f32 v58, v58, 0, v60
	v_max3_f32 v58, v58, v61, v82
	s_nop 1
	v_mov_b32_dpp v60, v58 quad_perm:[1,0,3,2] row_mask:0xf bank_mask:0xf bound_ctrl:1
	v_max_f32_e32 v60, v60, v60
	v_max_f32_e32 v58, v58, v60
	s_nop 1
	v_mov_b32_dpp v60, v58 quad_perm:[2,3,0,1] row_mask:0xf bank_mask:0xf bound_ctrl:1
	v_max_f32_e32 v60, v60, v60
	v_max_f32_e32 v58, v58, v60
	s_nop 1
	v_mov_b32_dpp v60, v58 row_half_mirror row_mask:0xf bank_mask:0xf bound_ctrl:1
	v_max_f32_e32 v60, v60, v60
	v_max_f32_e32 v58, v58, v60
	s_nop 1
	v_mov_b32_dpp v60, v58 row_mirror row_mask:0xf bank_mask:0xf bound_ctrl:1
	v_max_f32_e32 v60, v60, v60
	v_max_f32_e32 v58, v58, v60
	s_nop 0
	v_readlane_b32 s24, v58, 32
	v_readlane_b32 s25, v58, 48
	v_readlane_b32 s22, v58, 0
	v_readlane_b32 s23, v58, 16
	v_max_f32_e64 v58, s25, s25
	v_max_f32_e64 v60, s24, s24
	v_mov_b32_e32 v61, s23
	v_max_f32_e32 v58, v60, v58
	v_max3_f32 v58, s22, v61, v58
	v_div_scale_f32 v82, s[22:23], v58, v58, s11
	v_rcp_f32_e32 v83, v82
	v_div_scale_f32 v84, vcc, s11, v58, s11
	v_lshl_add_u64 v[60:61], v[4:5], 0, s[0:1]
	v_fma_f32 v85, -v82, v83, 1.0
	v_fmac_f32_e32 v83, v85, v83
	v_mul_f32_e32 v85, v84, v83
	v_fma_f32 v86, -v82, v85, v84
	v_fmac_f32_e32 v85, v86, v83
	v_fma_f32 v82, -v82, v85, v84
	v_div_fmas_f32 v82, v82, v83, v85
	v_div_fixup_f32 v82, v82, v58, s11
	v_cmp_lt_f32_e32 vcc, 0, v58
	s_nop 1
	v_cndmask_b32_e32 v82, 0, v82, vcc
	v_mul_f32_e32 v59, v59, v82
	v_mul_f32_e32 v73, v73, v82
	v_mul_f32_e32 v63, v63, v82
	v_mul_f32_e32 v62, v62, v82
	v_rndne_f32_e32 v59, v59
	v_rndne_f32_e32 v73, v73
	v_rndne_f32_e32 v63, v63
	v_mul_f32_e32 v64, v64, v82
	v_mul_f32_e32 v65, v65, v82
	v_rndne_f32_e32 v62, v62
	v_cvt_i32_f32_e32 v59, v59
	v_cvt_i32_f32_e32 v73, v73
	v_cvt_i32_f32_e32 v63, v63
	v_mul_f32_e32 v66, v66, v82
	v_mul_f32_e32 v67, v67, v82
	v_rndne_f32_e32 v64, v64
	v_rndne_f32_e32 v65, v65
	v_cvt_i32_f32_e32 v62, v62
	v_rndne_f32_e32 v66, v66
	v_rndne_f32_e32 v67, v67
	v_cvt_i32_f32_e32 v64, v64
	v_cvt_i32_f32_e32 v65, v65
	v_cvt_i32_f32_e32 v66, v66
	v_cvt_i32_f32_e32 v67, v67
	v_add_u32_e32 v83, v59, v73
	v_add_u32_e32 v59, 0x80, v59
	v_lshl_add_u32 v73, v73, 8, v71
	v_lshlrev_b32_e32 v85, 24, v63
	v_lshl_add_u32 v84, v62, 16, v72
	v_add3_u32 v62, v83, v62, v63
	v_or_b32_e32 v59, v73, v59
	v_xor_b32_e32 v63, 0x80000000, v85
	v_add_u32_e32 v86, 0x80, v64
	v_or3_b32 v59, v59, v84, v63
	v_add3_u32 v62, v62, v64, v65
	v_mul_f32_e32 v63, v74, v82
	v_mul_f32_e32 v64, v75, v82
	v_lshl_add_u32 v87, v65, 8, v71
	v_lshl_add_u32 v88, v66, 16, v72
	global_store_dword v[60:61], v59, off
	v_add3_u32 v59, v62, v66, v67
	v_rndne_f32_e32 v63, v63
	v_rndne_f32_e32 v64, v64
	v_mul_f32_e32 v65, v76, v82
	v_mul_f32_e32 v66, v77, v82
	v_cvt_i32_f32_e32 v63, v63
	v_cvt_i32_f32_e32 v64, v64
	v_rndne_f32_e32 v65, v65
	v_rndne_f32_e32 v66, v66
	v_lshlrev_b32_e32 v62, 24, v67
	v_cvt_i32_f32_e32 v65, v65
	v_cvt_i32_f32_e32 v66, v66
	v_or_b32_e32 v73, v87, v86
	v_xor_b32_e32 v62, 0x80000000, v62
	v_or3_b32 v62, v73, v88, v62
	global_store_dword v[60:61], v62, off offset:256
	v_add3_u32 v59, v59, v63, v64
	v_add_u32_e32 v62, 0x80, v63
	v_lshl_add_u32 v63, v64, 8, v71
	v_add3_u32 v59, v59, v65, v66
	v_or_b32_e32 v62, v63, v62
	v_lshl_add_u32 v63, v65, 16, v72
	v_lshlrev_b32_e32 v64, 24, v66
	v_mul_f32_e32 v65, v78, v82
	v_mul_f32_e32 v66, v79, v82
	v_rndne_f32_e32 v65, v65
	v_rndne_f32_e32 v66, v66
	v_mul_f32_e32 v67, v80, v82
	v_mul_f32_e32 v73, v81, v82
	v_cvt_i32_f32_e32 v65, v65
	v_cvt_i32_f32_e32 v66, v66
	v_rndne_f32_e32 v67, v67
	v_rndne_f32_e32 v73, v73
	v_cvt_i32_f32_e32 v67, v67
	v_cvt_i32_f32_e32 v73, v73
	v_add3_u32 v59, v59, v65, v66
	v_xor_b32_e32 v64, 0x80000000, v64
	v_or3_b32 v62, v62, v63, v64
	v_add3_u32 v59, v59, v67, v73
	v_cvt_f32_i32_e32 v59, v59
	global_store_dword v[60:61], v62, off offset:512
	v_add_u32_e32 v62, 0x80, v65
	v_lshl_add_u32 v63, v66, 8, v71
	v_add_f32_dpp v59, v59, v59 quad_perm:[1,0,3,2] row_mask:0xf bank_mask:0xf bound_ctrl:1
	v_lshlrev_b32_e32 v64, 24, v73
	v_or_b32_e32 v62, v63, v62
	v_add_f32_dpp v59, v59, v59 quad_perm:[2,3,0,1] row_mask:0xf bank_mask:0xf bound_ctrl:1
	v_lshl_add_u32 v63, v67, 16, v72
	v_xor_b32_e32 v64, 0x80000000, v64
	v_add_f32_dpp v59, v59, v59 row_half_mirror row_mask:0xf bank_mask:0xf bound_ctrl:1
	v_or3_b32 v62, v62, v63, v64
	global_store_dword v[60:61], v62, off offset:768
	v_add_f32_dpp v59, v59, v59 row_mirror row_mask:0xf bank_mask:0xf bound_ctrl:1
	s_nop 0
	v_readlane_b32 s22, v59, 0
	v_readlane_b32 s25, v59, 16
	v_readlane_b32 s23, v59, 32
	v_readlane_b32 s24, v59, 48
	s_and_saveexec_b64 s[0:1], s[2:3]
	s_cbranch_execz .LBB0_1596
	v_mov_b32_e32 v59, s25
	s_lshl_b64 s[20:21], s[20:21], 3
	v_add_f32_e32 v59, s22, v59
	s_add_u32 s20, s35, s20
	v_add_f32_e32 v59, s23, v59
	s_addc_u32 s21, s36, s21
	v_mul_f32_e32 v58, 0x3c010204, v58
	v_add_f32_e32 v59, s24, v59
	global_store_dwordx2 v69, v[58:59], s[20:21]
	s_branch .LBB0_1596
